# v109: v106 plus write-through (sc1) stores for the K / V cache outputs (f32, written once, never re-read in the launch)
# baseline (speedup 1.0000x reference)
.LBB0_411:
	s_andn2_b64 vcc, exec, s[2:3]
	s_cbranch_vccnz .LBB0_561
	s_mov_b64 s[2:3], -1
	s_cmp_lg_u32 s47, 1
	v_ashrrev_i32_e32 v187, 31, v186
	s_cbranch_scc0 .LBB0_551
	s_ashr_i32 s42, s48, 2
	s_cmp_gt_u32 s48, 3
	s_cselect_b64 s[14:15], -1, 0
	v_and_b32_e32 v130, -2, v186
	s_lshl_b32 s10, s48, 8
	v_ashrrev_i32_e32 v131, 31, v130
	s_and_b32 s10, s10, 0x300
	v_and_b32_e32 v0, 1, v179
	v_cmp_gt_i32_e64 s[12:13], s65, v186
	v_lshlrev_b64 v[130:131], 1, v[130:131]
	v_lshlrev_b64 v[150:151], 11, v[186:187]
	s_or_b32 s10, s10, s68
	v_cmp_eq_u32_e64 s[8:9], 0, v0
	v_lshlrev_b32_e32 v0, 2, v0
	s_and_b64 s[2:3], s[22:23], s[12:13]
	v_lshlrev_b64 v[144:145], 12, v[186:187]
	v_lshl_add_u64 v[148:149], s[44:45], 0, v[130:131]
	v_lshl_add_u64 v[142:143], s[78:79], 0, v[150:151]
	v_lshl_add_u64 v[140:141], s[0:1], 0, v[130:131]
	v_lshl_add_u64 v[146:147], s[96:97], 0, v[150:151]
	v_lshl_add_u32 v138, v239, 3, s10
	s_mov_b64 s[10:11], -1
	s_and_b64 vcc, exec, s[14:15]
	s_cbranch_vccz .LBB0_434
	s_mov_b64 s[40:41], -1
	s_mov_b64 s[10:11], 0
	s_cmp_lt_i32 s42, 2
	s_mov_b64 s[38:39], 0
	s_cbranch_scc1 .LBB0_422
	s_cmp_eq_u32 s42, 2
	s_mov_b64 s[38:39], -1
	s_cbranch_scc0 .LBB0_419
	s_and_saveexec_b64 s[38:39], s[2:3]
	s_cbranch_execz .LBB0_418
	v_readlane_b32 s40, v255, 1
	v_readlane_b32 s41, v255, 2
	v_ashrrev_i32_e32 v139, 31, v138
	s_nop 0
	v_lshl_add_u64 v[130:131], s[40:41], 0, v[144:145]
	v_lshl_add_u64 v[130:131], v[138:139], 2, v[130:131]
	global_store_dwordx4 v[130:131], v[126:129], off sc1
	global_store_dwordx4 v[130:131], v[122:125], off offset:16 sc1

.LBB0_427:
	s_andn2_b64 vcc, exec, s[10:11]
	s_cbranch_vccnz .LBB0_431
	s_and_saveexec_b64 s[10:11], s[12:13]
	s_cbranch_execz .LBB0_430
	v_readlane_b32 s38, v255, 59
	v_readlane_b32 s39, v255, 60
	v_ashrrev_i32_e32 v139, 31, v138
	s_nop 0
	v_lshl_add_u64 v[130:131], s[38:39], 0, v[144:145]
	v_lshl_add_u64 v[130:131], v[138:139], 2, v[130:131]
	global_store_dwordx4 v[130:131], v[126:129], off sc1
	global_store_dwordx4 v[130:131], v[122:125], off offset:16 sc1

.LBB0_436:
	s_nop 1
	v_cndmask_b32_e64 v130, 0, 1, s[14:15]
	v_add_u32_e32 v152, 0x80, v138
	v_cmp_ne_u32_e64 s[10:11], 1, v130
	s_andn2_b64 vcc, exec, s[14:15]
	s_mov_b64 s[14:15], -1
	s_cbranch_vccnz .LBB0_457
	s_mov_b64 s[40:41], -1
	s_mov_b64 s[14:15], 0
	s_cmp_lt_i32 s42, 2
	s_mov_b64 s[38:39], 0
	s_cbranch_scc1 .LBB0_445
	s_cmp_eq_u32 s42, 2
	s_mov_b64 s[38:39], -1
	s_cbranch_scc0 .LBB0_442
	s_and_saveexec_b64 s[38:39], s[2:3]
	s_cbranch_execz .LBB0_441
	v_readlane_b32 s2, v255, 1
	v_readlane_b32 s3, v255, 2
	s_nop 1
	v_lshl_add_u64 v[130:131], s[2:3], 0, v[144:145]
	v_lshl_add_u64 v[130:131], v[138:139], 2, v[130:131]
	global_store_dwordx4 v[130:131], v[118:121], off offset:512 sc1
	global_store_dwordx4 v[130:131], v[114:117], off offset:528 sc1

.LBB0_450:
	s_andn2_b64 vcc, exec, s[2:3]
	s_cbranch_vccnz .LBB0_454
	s_and_saveexec_b64 s[2:3], s[12:13]
	s_cbranch_execz .LBB0_453
	v_readlane_b32 s12, v255, 59
	v_readlane_b32 s13, v255, 60
	s_nop 1
	v_lshl_add_u64 v[130:131], s[12:13], 0, v[144:145]
	v_lshl_add_u64 v[130:131], v[138:139], 2, v[130:131]
	global_store_dwordx4 v[130:131], v[118:121], off offset:512 sc1
	global_store_dwordx4 v[130:131], v[114:117], off offset:528 sc1

.LBB0_459:
	s_nop 1
	v_add_u32_e32 v130, 16, v186
	v_and_b32_e32 v132, -2, v130
	s_movk_i32 s2, 0x1ff0
	v_ashrrev_i32_e32 v131, 31, v130
	v_ashrrev_i32_e32 v133, 31, v132
	v_cmp_gt_i32_e64 s[12:13], s2, v186
	v_lshlrev_b64 v[132:133], 1, v[132:133]
	v_lshlrev_b64 v[150:151], 11, v[130:131]
	s_and_b64 s[2:3], s[22:23], s[12:13]
	v_lshlrev_b64 v[144:145], 12, v[130:131]
	v_lshl_add_u64 v[148:149], s[44:45], 0, v[132:133]
	v_lshl_add_u64 v[142:143], s[78:79], 0, v[150:151]
	v_lshl_add_u64 v[140:141], s[0:1], 0, v[132:133]
	v_lshl_add_u64 v[146:147], s[96:97], 0, v[150:151]
	s_and_b64 vcc, exec, s[10:11]
	s_mov_b64 s[14:15], -1
	s_cbranch_vccnz .LBB0_468
	s_mov_b64 s[40:41], -1
	s_mov_b64 s[14:15], 0
	s_cmp_lt_i32 s42, 2
	s_mov_b64 s[38:39], 0
	s_cbranch_scc1 .LBB0_567
	s_cmp_eq_u32 s42, 2
	s_mov_b64 s[38:39], -1
	s_cbranch_scc0 .LBB0_465
	s_and_saveexec_b64 s[38:39], s[2:3]
	s_cbranch_execz .LBB0_464
	v_readlane_b32 s40, v255, 1
	v_readlane_b32 s41, v255, 2
	s_nop 1
	v_lshl_add_u64 v[130:131], s[40:41], 0, v[144:145]
	v_lshl_add_u64 v[130:131], v[138:139], 2, v[130:131]
	global_store_dwordx4 v[130:131], v[110:113], off sc1
	global_store_dwordx4 v[130:131], v[106:109], off offset:16 sc1

.LBB0_472:
	s_nop 1
	v_add_u32_e32 v130, 32, v186
	v_and_b32_e32 v132, -2, v130
	s_movk_i32 s2, 0x1fe0
	v_ashrrev_i32_e32 v131, 31, v130
	v_ashrrev_i32_e32 v133, 31, v132
	v_cmp_gt_i32_e64 s[12:13], s2, v186
	v_lshlrev_b64 v[132:133], 1, v[132:133]
	v_lshlrev_b64 v[150:151], 11, v[130:131]
	s_and_b64 s[2:3], s[22:23], s[12:13]
	v_lshlrev_b64 v[144:145], 12, v[130:131]
	v_lshl_add_u64 v[148:149], s[44:45], 0, v[132:133]
	v_lshl_add_u64 v[142:143], s[78:79], 0, v[150:151]
	v_lshl_add_u64 v[140:141], s[0:1], 0, v[132:133]
	v_lshl_add_u64 v[146:147], s[96:97], 0, v[150:151]
	s_and_b64 vcc, exec, s[10:11]
	s_mov_b64 s[14:15], -1
	s_cbranch_vccnz .LBB0_481
	s_mov_b64 s[40:41], -1
	s_mov_b64 s[14:15], 0
	s_cmp_lt_i32 s42, 2
	s_mov_b64 s[38:39], 0
	s_cbranch_scc1 .LBB0_588
	s_cmp_eq_u32 s42, 2
	s_mov_b64 s[38:39], -1
	s_cbranch_scc0 .LBB0_478
	s_and_saveexec_b64 s[38:39], s[2:3]
	s_cbranch_execz .LBB0_477
	v_readlane_b32 s40, v255, 1
	v_readlane_b32 s41, v255, 2
	s_nop 1
	v_lshl_add_u64 v[130:131], s[40:41], 0, v[144:145]
	v_lshl_add_u64 v[130:131], v[138:139], 2, v[130:131]
	global_store_dwordx4 v[130:131], v[94:97], off sc1
	global_store_dwordx4 v[130:131], v[90:93], off offset:16 sc1

.LBB0_485:
	s_nop 1
	v_add_u32_e32 v130, 48, v186
	v_and_b32_e32 v132, -2, v130
	s_movk_i32 s2, 0x1fd0
	v_ashrrev_i32_e32 v131, 31, v130
	v_ashrrev_i32_e32 v133, 31, v132
	v_cmp_gt_i32_e64 s[12:13], s2, v186
	v_lshlrev_b64 v[132:133], 1, v[132:133]
	v_lshlrev_b64 v[150:151], 11, v[130:131]
	s_and_b64 s[2:3], s[22:23], s[12:13]
	v_lshlrev_b64 v[144:145], 12, v[130:131]
	v_lshl_add_u64 v[148:149], s[44:45], 0, v[132:133]
	v_lshl_add_u64 v[142:143], s[78:79], 0, v[150:151]
	v_lshl_add_u64 v[140:141], s[0:1], 0, v[132:133]
	v_lshl_add_u64 v[146:147], s[96:97], 0, v[150:151]
	s_and_b64 vcc, exec, s[10:11]
	s_mov_b64 s[14:15], -1
	s_cbranch_vccnz .LBB0_494
	s_mov_b64 s[40:41], -1
	s_mov_b64 s[14:15], 0
	s_cmp_lt_i32 s42, 2
	s_mov_b64 s[38:39], 0
	s_cbranch_scc1 .LBB0_609
	s_cmp_eq_u32 s42, 2
	s_mov_b64 s[38:39], -1
	s_cbranch_scc0 .LBB0_491
	s_and_saveexec_b64 s[38:39], s[2:3]
	s_cbranch_execz .LBB0_490
	v_readlane_b32 s40, v255, 1
	v_readlane_b32 s41, v255, 2
	s_nop 1
	v_lshl_add_u64 v[130:131], s[40:41], 0, v[144:145]
	v_lshl_add_u64 v[130:131], v[138:139], 2, v[130:131]
	global_store_dwordx4 v[130:131], v[78:81], off sc1
	global_store_dwordx4 v[130:131], v[74:77], off offset:16 sc1

.LBB0_498:
	s_nop 1
	v_add_u32_e32 v130, 0x80, v186
	v_and_b32_e32 v132, -2, v130
	s_movk_i32 s2, 0x1f80
	v_ashrrev_i32_e32 v131, 31, v130
	v_ashrrev_i32_e32 v133, 31, v132
	v_cmp_gt_i32_e64 s[12:13], s2, v186
	v_lshlrev_b64 v[132:133], 1, v[132:133]
	v_lshlrev_b64 v[150:151], 11, v[130:131]
	s_and_b64 s[2:3], s[22:23], s[12:13]
	v_lshlrev_b64 v[144:145], 12, v[130:131]
	v_lshl_add_u64 v[148:149], s[44:45], 0, v[132:133]
	v_lshl_add_u64 v[142:143], s[78:79], 0, v[150:151]
	v_lshl_add_u64 v[140:141], s[0:1], 0, v[132:133]
	v_lshl_add_u64 v[146:147], s[96:97], 0, v[150:151]
	s_and_b64 vcc, exec, s[10:11]
	s_mov_b64 s[14:15], -1
	s_cbranch_vccnz .LBB0_507
	s_mov_b64 s[40:41], -1
	s_mov_b64 s[14:15], 0
	s_cmp_lt_i32 s42, 2
	s_mov_b64 s[38:39], 0
	s_cbranch_scc1 .LBB0_630
	s_cmp_eq_u32 s42, 2
	s_mov_b64 s[38:39], -1
	s_cbranch_scc0 .LBB0_504
	s_and_saveexec_b64 s[38:39], s[2:3]
	s_cbranch_execz .LBB0_503
	v_readlane_b32 s40, v255, 1
	v_readlane_b32 s41, v255, 2
	s_nop 1
	v_lshl_add_u64 v[130:131], s[40:41], 0, v[144:145]
	v_lshl_add_u64 v[130:131], v[138:139], 2, v[130:131]
	global_store_dwordx4 v[130:131], v[62:65], off sc1
	global_store_dwordx4 v[130:131], v[58:61], off offset:16 sc1

.LBB0_511:
	s_nop 1
	v_add_u32_e32 v130, 0x90, v186
	v_and_b32_e32 v132, -2, v130
	s_movk_i32 s2, 0x1f70
	v_ashrrev_i32_e32 v131, 31, v130
	v_ashrrev_i32_e32 v133, 31, v132
	v_cmp_gt_i32_e64 s[12:13], s2, v186
	v_lshlrev_b64 v[132:133], 1, v[132:133]
	v_lshlrev_b64 v[150:151], 11, v[130:131]
	s_and_b64 s[2:3], s[22:23], s[12:13]
	v_lshlrev_b64 v[144:145], 12, v[130:131]
	v_lshl_add_u64 v[148:149], s[44:45], 0, v[132:133]
	v_lshl_add_u64 v[142:143], s[78:79], 0, v[150:151]
	v_lshl_add_u64 v[140:141], s[0:1], 0, v[132:133]
	v_lshl_add_u64 v[146:147], s[96:97], 0, v[150:151]
	s_and_b64 vcc, exec, s[10:11]
	s_mov_b64 s[14:15], -1
	s_cbranch_vccnz .LBB0_520
	s_mov_b64 s[40:41], -1
	s_mov_b64 s[14:15], 0
	s_cmp_lt_i32 s42, 2
	s_mov_b64 s[38:39], 0
	s_cbranch_scc1 .LBB0_651
	s_cmp_eq_u32 s42, 2
	s_mov_b64 s[38:39], -1
	s_cbranch_scc0 .LBB0_517
	s_and_saveexec_b64 s[38:39], s[2:3]
	s_cbranch_execz .LBB0_516
	v_readlane_b32 s40, v255, 1
	v_readlane_b32 s41, v255, 2
	s_nop 1
	v_lshl_add_u64 v[130:131], s[40:41], 0, v[144:145]
	v_lshl_add_u64 v[130:131], v[138:139], 2, v[130:131]
	global_store_dwordx4 v[130:131], v[46:49], off sc1
	global_store_dwordx4 v[130:131], v[42:45], off offset:16 sc1

.LBB0_524:
	s_nop 1
	v_add_u32_e32 v130, 0xa0, v186
	v_and_b32_e32 v132, -2, v130
	s_movk_i32 s2, 0x1f60
	v_ashrrev_i32_e32 v131, 31, v130
	v_ashrrev_i32_e32 v133, 31, v132
	v_cmp_gt_i32_e64 s[12:13], s2, v186
	v_lshlrev_b64 v[132:133], 1, v[132:133]
	v_lshlrev_b64 v[150:151], 11, v[130:131]
	s_and_b64 s[2:3], s[22:23], s[12:13]
	v_lshlrev_b64 v[144:145], 12, v[130:131]
	v_lshl_add_u64 v[148:149], s[44:45], 0, v[132:133]
	v_lshl_add_u64 v[142:143], s[78:79], 0, v[150:151]
	v_lshl_add_u64 v[140:141], s[0:1], 0, v[132:133]
	v_lshl_add_u64 v[146:147], s[96:97], 0, v[150:151]
	s_and_b64 vcc, exec, s[10:11]
	s_mov_b64 s[14:15], -1
	s_cbranch_vccnz .LBB0_533
	s_mov_b64 s[40:41], -1
	s_mov_b64 s[14:15], 0
	s_cmp_lt_i32 s42, 2
	s_mov_b64 s[38:39], 0
	s_cbranch_scc1 .LBB0_672
	s_cmp_eq_u32 s42, 2
	s_mov_b64 s[38:39], -1
	s_cbranch_scc0 .LBB0_530
	s_and_saveexec_b64 s[38:39], s[2:3]
	s_cbranch_execz .LBB0_529
	v_readlane_b32 s40, v255, 1
	v_readlane_b32 s41, v255, 2
	s_nop 1
	v_lshl_add_u64 v[130:131], s[40:41], 0, v[144:145]
	v_lshl_add_u64 v[130:131], v[138:139], 2, v[130:131]
	global_store_dwordx4 v[130:131], v[30:33], off sc1
	global_store_dwordx4 v[130:131], v[26:29], off offset:16 sc1

.LBB0_537:
	s_nop 1
	v_add_u32_e32 v130, 0xb0, v186
	v_and_b32_e32 v132, -2, v130
	s_movk_i32 s2, 0x1f50
	v_ashrrev_i32_e32 v131, 31, v130
	v_ashrrev_i32_e32 v133, 31, v132
	v_cmp_gt_i32_e64 s[12:13], s2, v186
	v_lshlrev_b64 v[132:133], 1, v[132:133]
	v_lshlrev_b64 v[150:151], 11, v[130:131]
	s_and_b64 s[2:3], s[22:23], s[12:13]
	v_lshlrev_b64 v[144:145], 12, v[130:131]
	v_lshl_add_u64 v[148:149], s[44:45], 0, v[132:133]
	v_lshl_add_u64 v[142:143], s[78:79], 0, v[150:151]
	v_lshl_add_u64 v[140:141], s[0:1], 0, v[132:133]
	v_lshl_add_u64 v[146:147], s[96:97], 0, v[150:151]
	s_and_b64 vcc, exec, s[10:11]
	s_mov_b64 s[14:15], -1
	s_cbranch_vccnz .LBB0_546
	s_mov_b64 s[40:41], -1
	s_mov_b64 s[14:15], 0
	s_cmp_lt_i32 s42, 2
	s_mov_b64 s[38:39], 0
	s_cbranch_scc1 .LBB0_693
	s_cmp_eq_u32 s42, 2
	s_mov_b64 s[38:39], -1
	s_cbranch_scc0 .LBB0_543
	s_and_saveexec_b64 s[38:39], s[2:3]
	s_cbranch_execz .LBB0_542
	v_readlane_b32 s40, v255, 1
	v_readlane_b32 s41, v255, 2
	s_nop 1
	v_lshl_add_u64 v[130:131], s[40:41], 0, v[144:145]
	v_lshl_add_u64 v[130:131], v[138:139], 2, v[130:131]
	global_store_dwordx4 v[130:131], v[14:17], off sc1
	global_store_dwordx4 v[130:131], v[10:13], off offset:16 sc1

.LBB0_572:
	s_andn2_b64 vcc, exec, s[38:39]
	s_cbranch_vccnz .LBB0_576
	s_and_saveexec_b64 s[38:39], s[12:13]
	s_cbranch_execz .LBB0_575
	v_readlane_b32 s40, v255, 59
	v_readlane_b32 s41, v255, 60
	s_nop 1
	v_lshl_add_u64 v[130:131], s[40:41], 0, v[144:145]
	v_lshl_add_u64 v[130:131], v[138:139], 2, v[130:131]
	global_store_dwordx4 v[130:131], v[110:113], off sc1
	global_store_dwordx4 v[130:131], v[106:109], off offset:16 sc1

.LBB0_580:
	s_mov_b64 s[40:41], -1
	s_mov_b64 s[14:15], 0
	s_cmp_lt_i32 s42, 2
	s_mov_b64 s[38:39], 0
	s_cbranch_scc1 .LBB0_714
	s_cmp_eq_u32 s42, 2
	s_mov_b64 s[38:39], -1
	s_cbranch_scc0 .LBB0_585
	s_and_saveexec_b64 s[38:39], s[2:3]
	s_cbranch_execz .LBB0_584
	v_readlane_b32 s2, v255, 1
	v_readlane_b32 s3, v255, 2
	s_nop 1
	v_lshl_add_u64 v[130:131], s[2:3], 0, v[144:145]
	v_lshl_add_u64 v[130:131], v[138:139], 2, v[130:131]
	global_store_dwordx4 v[130:131], v[102:105], off offset:512 sc1
	global_store_dwordx4 v[130:131], v[98:101], off offset:528 sc1

.LBB0_593:
	s_andn2_b64 vcc, exec, s[38:39]
	s_cbranch_vccnz .LBB0_597
	s_and_saveexec_b64 s[38:39], s[12:13]
	s_cbranch_execz .LBB0_596
	v_readlane_b32 s40, v255, 59
	v_readlane_b32 s41, v255, 60
	s_nop 1
	v_lshl_add_u64 v[130:131], s[40:41], 0, v[144:145]
	v_lshl_add_u64 v[130:131], v[138:139], 2, v[130:131]
	global_store_dwordx4 v[130:131], v[94:97], off sc1
	global_store_dwordx4 v[130:131], v[90:93], off offset:16 sc1

.LBB0_601:
	s_mov_b64 s[40:41], -1
	s_mov_b64 s[14:15], 0
	s_cmp_lt_i32 s42, 2
	s_mov_b64 s[38:39], 0
	s_cbranch_scc1 .LBB0_726
	s_cmp_eq_u32 s42, 2
	s_mov_b64 s[38:39], -1
	s_cbranch_scc0 .LBB0_606
	s_and_saveexec_b64 s[38:39], s[2:3]
	s_cbranch_execz .LBB0_605
	v_readlane_b32 s2, v255, 1
	v_readlane_b32 s3, v255, 2
	s_nop 1
	v_lshl_add_u64 v[130:131], s[2:3], 0, v[144:145]
	v_lshl_add_u64 v[130:131], v[138:139], 2, v[130:131]
	global_store_dwordx4 v[130:131], v[86:89], off offset:512 sc1
	global_store_dwordx4 v[130:131], v[82:85], off offset:528 sc1

.LBB0_614:
	s_andn2_b64 vcc, exec, s[38:39]
	s_cbranch_vccnz .LBB0_618
	s_and_saveexec_b64 s[38:39], s[12:13]
	s_cbranch_execz .LBB0_617
	v_readlane_b32 s40, v255, 59
	v_readlane_b32 s41, v255, 60
	s_nop 1
	v_lshl_add_u64 v[130:131], s[40:41], 0, v[144:145]
	v_lshl_add_u64 v[130:131], v[138:139], 2, v[130:131]
	global_store_dwordx4 v[130:131], v[78:81], off sc1
	global_store_dwordx4 v[130:131], v[74:77], off offset:16 sc1

.LBB0_622:
	s_mov_b64 s[40:41], -1
	s_mov_b64 s[14:15], 0
	s_cmp_lt_i32 s42, 2
	s_mov_b64 s[38:39], 0
	s_cbranch_scc1 .LBB0_738
	s_cmp_eq_u32 s42, 2
	s_mov_b64 s[38:39], -1
	s_cbranch_scc0 .LBB0_627
	s_and_saveexec_b64 s[38:39], s[2:3]
	s_cbranch_execz .LBB0_626
	v_readlane_b32 s2, v255, 1
	v_readlane_b32 s3, v255, 2
	s_nop 1
	v_lshl_add_u64 v[130:131], s[2:3], 0, v[144:145]
	v_lshl_add_u64 v[130:131], v[138:139], 2, v[130:131]
	global_store_dwordx4 v[130:131], v[70:73], off offset:512 sc1
	global_store_dwordx4 v[130:131], v[66:69], off offset:528 sc1

.LBB0_635:
	s_andn2_b64 vcc, exec, s[38:39]
	s_cbranch_vccnz .LBB0_639
	s_and_saveexec_b64 s[38:39], s[12:13]
	s_cbranch_execz .LBB0_638
	v_readlane_b32 s40, v255, 59
	v_readlane_b32 s41, v255, 60
	s_nop 1
	v_lshl_add_u64 v[130:131], s[40:41], 0, v[144:145]
	v_lshl_add_u64 v[130:131], v[138:139], 2, v[130:131]
	global_store_dwordx4 v[130:131], v[62:65], off sc1
	global_store_dwordx4 v[130:131], v[58:61], off offset:16 sc1

.LBB0_643:
	s_mov_b64 s[40:41], -1
	s_mov_b64 s[14:15], 0
	s_cmp_lt_i32 s42, 2
	s_mov_b64 s[38:39], 0
	s_cbranch_scc1 .LBB0_750
	s_cmp_eq_u32 s42, 2
	s_mov_b64 s[38:39], -1
	s_cbranch_scc0 .LBB0_648
	s_and_saveexec_b64 s[38:39], s[2:3]
	s_cbranch_execz .LBB0_647
	v_readlane_b32 s2, v255, 1
	v_readlane_b32 s3, v255, 2
	s_nop 1
	v_lshl_add_u64 v[130:131], s[2:3], 0, v[144:145]
	v_lshl_add_u64 v[130:131], v[138:139], 2, v[130:131]
	global_store_dwordx4 v[130:131], v[54:57], off offset:512 sc1
	global_store_dwordx4 v[130:131], v[50:53], off offset:528 sc1

.LBB0_656:
	s_andn2_b64 vcc, exec, s[38:39]
	s_cbranch_vccnz .LBB0_660
	s_and_saveexec_b64 s[38:39], s[12:13]
	s_cbranch_execz .LBB0_659
	v_readlane_b32 s40, v255, 59
	v_readlane_b32 s41, v255, 60
	s_nop 1
	v_lshl_add_u64 v[130:131], s[40:41], 0, v[144:145]
	v_lshl_add_u64 v[130:131], v[138:139], 2, v[130:131]
	global_store_dwordx4 v[130:131], v[46:49], off sc1
	global_store_dwordx4 v[130:131], v[42:45], off offset:16 sc1

.LBB0_664:
	s_mov_b64 s[40:41], -1
	s_mov_b64 s[14:15], 0
	s_cmp_lt_i32 s42, 2
	s_mov_b64 s[38:39], 0
	s_cbranch_scc1 .LBB0_762
	s_cmp_eq_u32 s42, 2
	s_mov_b64 s[38:39], -1
	s_cbranch_scc0 .LBB0_669
	s_and_saveexec_b64 s[38:39], s[2:3]
	s_cbranch_execz .LBB0_668
	v_readlane_b32 s2, v255, 1
	v_readlane_b32 s3, v255, 2
	s_nop 1
	v_lshl_add_u64 v[130:131], s[2:3], 0, v[144:145]
	v_lshl_add_u64 v[130:131], v[138:139], 2, v[130:131]
	global_store_dwordx4 v[130:131], v[38:41], off offset:512 sc1
	global_store_dwordx4 v[130:131], v[34:37], off offset:528 sc1

.LBB0_677:
	s_andn2_b64 vcc, exec, s[38:39]
	s_cbranch_vccnz .LBB0_681
	s_and_saveexec_b64 s[38:39], s[12:13]
	s_cbranch_execz .LBB0_680
	v_readlane_b32 s40, v255, 59
	v_readlane_b32 s41, v255, 60
	s_nop 1
	v_lshl_add_u64 v[130:131], s[40:41], 0, v[144:145]
	v_lshl_add_u64 v[130:131], v[138:139], 2, v[130:131]
	global_store_dwordx4 v[130:131], v[30:33], off sc1
	global_store_dwordx4 v[130:131], v[26:29], off offset:16 sc1

.LBB0_685:
	s_mov_b64 s[40:41], -1
	s_mov_b64 s[14:15], 0
	s_cmp_lt_i32 s42, 2
	s_mov_b64 s[38:39], 0
	s_cbranch_scc1 .LBB0_774
	s_cmp_eq_u32 s42, 2
	s_mov_b64 s[38:39], -1
	s_cbranch_scc0 .LBB0_690
	s_and_saveexec_b64 s[38:39], s[2:3]
	s_cbranch_execz .LBB0_689
	v_readlane_b32 s2, v255, 1
	v_readlane_b32 s3, v255, 2
	s_nop 1
	v_lshl_add_u64 v[130:131], s[2:3], 0, v[144:145]
	v_lshl_add_u64 v[130:131], v[138:139], 2, v[130:131]
	global_store_dwordx4 v[130:131], v[22:25], off offset:512 sc1
	global_store_dwordx4 v[130:131], v[18:21], off offset:528 sc1

.LBB0_698:
	s_andn2_b64 vcc, exec, s[38:39]
	s_cbranch_vccnz .LBB0_702
	s_and_saveexec_b64 s[38:39], s[12:13]
	s_cbranch_execz .LBB0_701
	v_readlane_b32 s40, v255, 59
	v_readlane_b32 s41, v255, 60
	s_nop 1
	v_lshl_add_u64 v[130:131], s[40:41], 0, v[144:145]
	v_lshl_add_u64 v[130:131], v[138:139], 2, v[130:131]
	global_store_dwordx4 v[130:131], v[14:17], off sc1
	global_store_dwordx4 v[130:131], v[10:13], off offset:16 sc1

.LBB0_706:
	s_mov_b64 s[38:39], -1
	s_mov_b64 s[10:11], 0
	s_cmp_lt_i32 s42, 2
	s_mov_b64 s[14:15], 0
	s_cbranch_scc1 .LBB0_786
	s_cmp_eq_u32 s42, 2
	s_mov_b64 s[14:15], -1
	s_cbranch_scc0 .LBB0_711
	s_and_saveexec_b64 s[14:15], s[2:3]
	s_cbranch_execz .LBB0_710
	v_readlane_b32 s2, v255, 1
	v_readlane_b32 s3, v255, 2
	s_nop 1
	v_lshl_add_u64 v[130:131], s[2:3], 0, v[144:145]
	v_lshl_add_u64 v[130:131], v[138:139], 2, v[130:131]
	global_store_dwordx4 v[130:131], v[6:9], off offset:512 sc1
	global_store_dwordx4 v[130:131], v[2:5], off offset:528 sc1

.LBB0_719:
	s_andn2_b64 vcc, exec, s[2:3]
	s_cbranch_vccnz .LBB0_723
	s_and_saveexec_b64 s[2:3], s[12:13]
	s_cbranch_execz .LBB0_722
	v_readlane_b32 s12, v255, 59
	v_readlane_b32 s13, v255, 60
	s_nop 1
	v_lshl_add_u64 v[130:131], s[12:13], 0, v[144:145]
	v_lshl_add_u64 v[130:131], v[138:139], 2, v[130:131]
	global_store_dwordx4 v[130:131], v[102:105], off offset:512 sc1
	global_store_dwordx4 v[130:131], v[98:101], off offset:528 sc1

.LBB0_731:
	s_andn2_b64 vcc, exec, s[2:3]
	s_cbranch_vccnz .LBB0_735
	s_and_saveexec_b64 s[2:3], s[12:13]
	s_cbranch_execz .LBB0_734
	v_readlane_b32 s12, v255, 59
	v_readlane_b32 s13, v255, 60
	s_nop 1
	v_lshl_add_u64 v[130:131], s[12:13], 0, v[144:145]
	v_lshl_add_u64 v[130:131], v[138:139], 2, v[130:131]
	global_store_dwordx4 v[130:131], v[86:89], off offset:512 sc1
	global_store_dwordx4 v[130:131], v[82:85], off offset:528 sc1

.LBB0_743:
	s_andn2_b64 vcc, exec, s[2:3]
	s_cbranch_vccnz .LBB0_747
	s_and_saveexec_b64 s[2:3], s[12:13]
	s_cbranch_execz .LBB0_746
	v_readlane_b32 s12, v255, 59
	v_readlane_b32 s13, v255, 60
	s_nop 1
	v_lshl_add_u64 v[130:131], s[12:13], 0, v[144:145]
	v_lshl_add_u64 v[130:131], v[138:139], 2, v[130:131]
	global_store_dwordx4 v[130:131], v[70:73], off offset:512 sc1
	global_store_dwordx4 v[130:131], v[66:69], off offset:528 sc1

.LBB0_755:
	s_andn2_b64 vcc, exec, s[2:3]
	s_cbranch_vccnz .LBB0_759
	s_and_saveexec_b64 s[2:3], s[12:13]
	s_cbranch_execz .LBB0_758
	v_readlane_b32 s12, v255, 59
	v_readlane_b32 s13, v255, 60
	s_nop 1
	v_lshl_add_u64 v[130:131], s[12:13], 0, v[144:145]
	v_lshl_add_u64 v[130:131], v[138:139], 2, v[130:131]
	global_store_dwordx4 v[130:131], v[54:57], off offset:512 sc1
	global_store_dwordx4 v[130:131], v[50:53], off offset:528 sc1

.LBB0_767:
	s_andn2_b64 vcc, exec, s[2:3]
	s_cbranch_vccnz .LBB0_771
	s_and_saveexec_b64 s[2:3], s[12:13]
	s_cbranch_execz .LBB0_770
	v_readlane_b32 s12, v255, 59
	v_readlane_b32 s13, v255, 60
	s_nop 1
	v_lshl_add_u64 v[130:131], s[12:13], 0, v[144:145]
	v_lshl_add_u64 v[130:131], v[138:139], 2, v[130:131]
	global_store_dwordx4 v[130:131], v[38:41], off offset:512 sc1
	global_store_dwordx4 v[130:131], v[34:37], off offset:528 sc1

.LBB0_779:
	s_andn2_b64 vcc, exec, s[2:3]
	s_cbranch_vccnz .LBB0_783
	s_and_saveexec_b64 s[2:3], s[12:13]
	s_cbranch_execz .LBB0_782
	v_readlane_b32 s12, v255, 59
	v_readlane_b32 s13, v255, 60
	s_nop 1
	v_lshl_add_u64 v[130:131], s[12:13], 0, v[144:145]
	v_lshl_add_u64 v[130:131], v[138:139], 2, v[130:131]
	global_store_dwordx4 v[130:131], v[22:25], off offset:512 sc1
	global_store_dwordx4 v[130:131], v[18:21], off offset:528 sc1

.LBB0_791:
	s_andn2_b64 vcc, exec, s[2:3]
	s_cbranch_vccnz .LBB0_795
	s_and_saveexec_b64 s[2:3], s[12:13]
	s_cbranch_execz .LBB0_794
	v_readlane_b32 s12, v255, 59
	v_readlane_b32 s13, v255, 60
	s_nop 1
	v_lshl_add_u64 v[130:131], s[12:13], 0, v[144:145]
	v_lshl_add_u64 v[130:131], v[138:139], 2, v[130:131]
	global_store_dwordx4 v[130:131], v[6:9], off offset:512 sc1
	global_store_dwordx4 v[130:131], v[2:5], off offset:528 sc1
